# FFN1 SwiGLU epilogue: 8 row-sum loads issued together, one wait instead of 7 serialized
# speedup vs baseline: 1.0006x; 1.0006x over previous
.LBB0_1158:
	s_ashr_i32 s13, s1, 4
	s_lshl_b32 s1, s1, 8
	v_mbcnt_lo_u32_b32 v50, -1, 0
	v_mbcnt_hi_u32_b32 v50, -1, v50
	s_add_i32 s1, s1, s72
	v_and_or_b32 v146, v50, 15, s1
	s_lshl_b32 s1, s0, 8
	v_lshrrev_b32_e32 v50, 1, v50
	s_or_b32 s1, s1, s82
	v_and_b32_e32 v154, 24, v50
	s_lshl_b32 s0, s0, 7
	v_or_b32_e32 v50, s1, v154
	s_or_b32 s0, s0, s82
	s_mul_hi_i32 s1, s13, 0xb000
	s_mul_i32 s13, s13, 0xb000
	s_add_u32 s20, s38, s13
	s_addc_u32 s21, s39, s1
	v_ashrrev_i32_e32 v51, 31, v50
	v_ashrrev_i32_e32 v147, 31, v146
	v_lshl_add_u64 v[50:51], v[50:51], 2, s[20:21]
	v_lshl_add_u64 v[152:153], v[146:147], 3, s[8:9]
	flat_load_dwordx4 v[66:69], v[50:51]
	flat_load_dwordx4 v[54:57], v[50:51] offset:16
	flat_load_dwordx4 v[62:65], v[50:51] offset:512
	s_nop 0
	flat_load_dwordx4 v[50:53], v[50:51] offset:528
	s_mov_b32 s20, 0x3fb8aa3b
	global_load_dwordx2 v[162:163], v[152:153], off
	global_load_dwordx2 v[184:185], v[152:153], off offset:128
	global_load_dwordx2 v[186:187], v[152:153], off offset:256
	global_load_dwordx2 v[188:189], v[152:153], off offset:384
	global_load_dwordx2 v[168:169], v[152:153], off offset:1024
	global_load_dwordx2 v[192:193], v[152:153], off offset:1152
	global_load_dwordx2 v[194:195], v[152:153], off offset:1280
	global_load_dwordx2 v[196:197], v[152:153], off offset:1408
	s_movk_i32 s13, 0x2c00
	s_waitcnt vmcnt(0) lgkmcnt(0)
	v_pk_mul_f32 v[148:149], v[68:69], s[20:21] op_sel_hi:[1,0]
	v_pk_mul_f32 v[150:151], v[66:67], s[20:21] op_sel_hi:[1,0]
	v_xor_b32_e32 v147, v162, v163
	v_ashrrev_i32_e32 v147, 31, v147
	v_ffbh_i32_e32 v155, v163
	v_add_u32_e32 v147, 32, v147
	v_add_u32_e32 v155, -1, v155
	v_min_u32_e32 v147, v155, v147
	v_lshlrev_b64 v[162:163], v147, v[162:163]
	v_min_u32_e32 v155, 1, v162
	v_or_b32_e32 v155, v163, v155
	v_mov_b64_e32 v[162:163], v[184:185]
	v_cvt_f32_i32_e32 v155, v155
	v_sub_u32_e32 v147, 32, v147
	v_ldexp_f32 v147, v155, v147
	v_mul_f32_e32 v167, 0x35800000, v147
	v_fmamk_f32 v167, v167, 0x3a000000, v180
	v_cmp_gt_f32_e32 vcc, s73, v167
	v_mul_f32_e32 v170, 0x4b800000, v167
	v_xor_b32_e32 v147, v162, v163
	v_ashrrev_i32_e32 v147, 31, v147
	v_ffbh_i32_e32 v155, v163
	v_add_u32_e32 v147, 32, v147
	v_add_u32_e32 v155, -1, v155
	v_min_u32_e32 v147, v155, v147
	v_lshlrev_b64 v[162:163], v147, v[162:163]
	v_min_u32_e32 v155, 1, v162
	v_or_b32_e32 v155, v163, v155
	v_mov_b64_e32 v[162:163], v[186:187]
	v_cvt_f32_i32_e32 v155, v155
	v_sub_u32_e32 v147, 32, v147
	v_cndmask_b32_e32 v167, v167, v170, vcc
	v_rsq_f32_e32 v167, v167
	v_ldexp_f32 v147, v155, v147
	v_mul_f32_e32 v165, 0x35800000, v147
	v_mul_f32_e32 v170, 0x45800000, v167
	v_cndmask_b32_e32 v170, v167, v170, vcc
	v_mul_f32_e32 v172, 0xbfb8aa3b, v170
	v_pk_fma_f32 v[174:175], v[140:141], v[172:173], v[148:149] op_sel_hi:[1,0,1] neg_lo:[0,0,1] neg_hi:[0,0,1]
	v_pk_fma_f32 v[176:177], v[138:139], v[172:173], v[150:151] op_sel_hi:[1,0,1] neg_lo:[0,0,1] neg_hi:[0,0,1]
	v_exp_f32_e32 v174, v174
	v_exp_f32_e32 v176, v176
	v_exp_f32_e32 v177, v177
	v_exp_f32_e32 v175, v175
	v_pk_fma_f32 v[134:135], v[134:135], v[170:171], v[50:51] op_sel_hi:[1,0,1]
	v_pk_fma_f32 v[136:137], v[136:137], v[170:171], v[52:53] op_sel_hi:[1,0,1]
	v_pk_add_f32 v[176:177], v[176:177], 1.0 op_sel_hi:[1,0]
	v_pk_add_f32 v[174:175], v[174:175], 1.0 op_sel_hi:[1,0]
	v_rcp_f32_e32 v176, v176
	v_rcp_f32_e32 v177, v177
	v_rcp_f32_e32 v174, v174
	v_rcp_f32_e32 v175, v175
	v_pk_fma_f32 v[138:139], v[138:139], v[170:171], v[66:67] op_sel_hi:[1,0,1]
	v_pk_fma_f32 v[142:143], v[142:143], v[170:171], v[62:63] op_sel_hi:[1,0,1]
	v_pk_fma_f32 v[140:141], v[140:141], v[170:171], v[68:69] op_sel_hi:[1,0,1]
	v_pk_fma_f32 v[144:145], v[144:145], v[170:171], v[64:65] op_sel_hi:[1,0,1]
	v_pk_mul_f32 v[138:139], v[138:139], v[142:143]
	v_pk_mul_f32 v[140:141], v[140:141], v[144:145]
	v_pk_mul_f32 v[138:139], v[138:139], v[176:177]
	v_pk_mul_f32 v[140:141], v[140:141], v[174:175]
	v_xor_b32_e32 v147, v162, v163
	v_ashrrev_i32_e32 v147, 31, v147
	v_ffbh_i32_e32 v155, v163
	v_add_u32_e32 v147, 32, v147
	v_add_u32_e32 v155, -1, v155
	v_min_u32_e32 v147, v155, v147
	v_lshlrev_b64 v[162:163], v147, v[162:163]
	v_min_u32_e32 v155, 1, v162
	v_or_b32_e32 v155, v163, v155
	v_mov_b64_e32 v[162:163], v[188:189]
	v_cvt_f32_i32_e32 v155, v155
	v_sub_u32_e32 v147, 32, v147
	v_ldexp_f32 v147, v155, v147
	v_mul_f32_e32 v164, 0x35800000, v147
	v_xor_b32_e32 v147, v162, v163
	v_ashrrev_i32_e32 v147, 31, v147
	v_ffbh_i32_e32 v155, v163
	v_add_u32_e32 v147, 32, v147
	v_add_u32_e32 v155, -1, v155
	v_min_u32_e32 v147, v155, v147
	v_lshlrev_b64 v[162:163], v147, v[162:163]
	v_min_u32_e32 v155, 1, v162
	v_or_b32_e32 v155, v163, v155
	v_cvt_f32_i32_e32 v155, v155
	v_sub_u32_e32 v147, 32, v147
	v_ldexp_f32 v147, v155, v147
	v_mul_f32_e32 v163, 0x35800000, v147
	v_xor_b32_e32 v147, v168, v169
	v_ashrrev_i32_e32 v147, 31, v147
	v_ffbh_i32_e32 v155, v169
	v_add_u32_e32 v147, 32, v147
	v_add_u32_e32 v155, -1, v155
	v_min_u32_e32 v147, v155, v147
	v_lshlrev_b64 v[168:169], v147, v[168:169]
	v_min_u32_e32 v155, 1, v168
	v_or_b32_e32 v155, v169, v155
	v_mov_b64_e32 v[168:169], v[192:193]
	v_cvt_f32_i32_e32 v155, v155
	v_sub_u32_e32 v147, 32, v147
	v_ldexp_f32 v147, v155, v147
	v_mul_f32_e32 v162, 0x35800000, v147
	v_xor_b32_e32 v147, v168, v169
	v_ashrrev_i32_e32 v147, 31, v147
	v_ffbh_i32_e32 v155, v169
	v_add_u32_e32 v147, 32, v147
	v_add_u32_e32 v155, -1, v155
	v_min_u32_e32 v147, v155, v147
	v_lshlrev_b64 v[168:169], v147, v[168:169]
	v_min_u32_e32 v155, 1, v168
	v_or_b32_e32 v155, v169, v155
	v_mov_b64_e32 v[168:169], v[194:195]
	v_cvt_f32_i32_e32 v155, v155
	v_mov_b64_e32 v[152:153], v[196:197]
	v_sub_u32_e32 v147, 32, v147
	v_ldexp_f32 v147, v155, v147
	v_mul_f32_e32 v161, 0x35800000, v147
	v_xor_b32_e32 v147, v168, v169
	v_ashrrev_i32_e32 v147, 31, v147
	v_ffbh_i32_e32 v155, v169
	v_add_u32_e32 v147, 32, v147
	v_add_u32_e32 v155, -1, v155
	v_min_u32_e32 v147, v155, v147
	v_lshlrev_b64 v[168:169], v147, v[168:169]
	v_min_u32_e32 v155, 1, v168
	v_or_b32_e32 v155, v169, v155
	v_cvt_f32_i32_e32 v155, v155
	v_sub_u32_e32 v147, 32, v147
	v_ffbh_i32_e32 v166, v153
	v_add_u32_e32 v166, -1, v166
	v_ldexp_f32 v147, v155, v147
	v_xor_b32_e32 v155, v152, v153
	v_ashrrev_i32_e32 v155, 31, v155
	v_add_u32_e32 v155, 32, v155
	v_min_u32_e32 v155, v166, v155
	v_lshlrev_b64 v[152:153], v155, v[152:153]
	v_min_u32_e32 v152, 1, v152
	v_or_b32_e32 v152, v153, v152
	v_cvt_f32_i32_e32 v152, v152
	v_sub_u32_e32 v153, 32, v155
	v_or_b32_e32 v168, s0, v154
	v_pk_mul_f32 v[154:155], v[54:55], s[20:21] op_sel_hi:[1,0]
	v_ldexp_f32 v152, v152, v153
	v_mul_f32_e32 v166, 0x35800000, v152
	v_pk_mul_f32 v[152:153], v[56:57], s[20:21] op_sel_hi:[1,0]
	v_ashrrev_i32_e32 v169, 31, v168
	v_pk_fma_f32 v[178:179], v[132:133], v[172:173], v[152:153] op_sel_hi:[1,0,1] neg_lo:[0,0,1] neg_hi:[0,0,1]
	v_pk_fma_f32 v[172:173], v[130:131], v[172:173], v[154:155] op_sel_hi:[1,0,1] neg_lo:[0,0,1] neg_hi:[0,0,1]
	v_exp_f32_e32 v178, v178
	v_exp_f32_e32 v172, v172
	v_exp_f32_e32 v173, v173
	v_exp_f32_e32 v179, v179
	v_pk_fma_f32 v[130:131], v[130:131], v[170:171], v[54:55] op_sel_hi:[1,0,1]
	v_pk_fma_f32 v[132:133], v[132:133], v[170:171], v[56:57] op_sel_hi:[1,0,1]
	v_pk_add_f32 v[172:173], v[172:173], 1.0 op_sel_hi:[1,0]
	v_pk_add_f32 v[178:179], v[178:179], 1.0 op_sel_hi:[1,0]
	v_rcp_f32_e32 v172, v172
	v_rcp_f32_e32 v173, v173
	v_rcp_f32_e32 v178, v178
	v_rcp_f32_e32 v179, v179
	v_pk_mul_f32 v[130:131], v[130:131], v[134:135]
	v_pk_mul_f32 v[132:133], v[132:133], v[136:137]
	v_pk_mul_f32 v[136:137], v[130:131], v[172:173]
	v_mov_b64_e32 v[130:131], s[10:11]
	v_pk_mul_f32 v[142:143], v[132:133], v[178:179]
	v_mad_i64_i32 v[134:135], s[0:1], v146, s13, v[130:131]
	v_lshlrev_b64 v[132:133], 1, v[168:169]
	v_lshl_add_u64 v[144:145], v[134:135], 0, v[132:133]
	v_cvt_pk_bf16_f32 v134, v138, v139
	v_cvt_pk_bf16_f32 v135, v140, v141
	v_cvt_pk_bf16_f32 v136, v136, v137
	v_cvt_pk_bf16_f32 v137, v142, v143
	flat_store_dwordx4 v[144:145], v[134:137]
	v_mul_f32_e32 v147, 0x35800000, v147
	s_mov_b64 s[20:21], -1
	v_fmamk_f32 v134, v165, 0x3a000000, v180
	v_cmp_gt_f32_e32 vcc, s73, v134
	v_mul_f32_e32 v135, 0x4b800000, v134
	s_nop 0
	v_cndmask_b32_e32 v134, v134, v135, vcc
	v_rsq_f32_e32 v134, v134
	s_nop 0
	v_mul_f32_e32 v135, 0x45800000, v134
	v_cndmask_b32_e32 v134, v134, v135, vcc
	v_mul_f32_e32 v136, 0xbfb8aa3b, v134
	v_pk_fma_f32 v[138:139], v[124:125], v[136:137], v[148:149] op_sel_hi:[1,0,1] neg_lo:[0,0,1] neg_hi:[0,0,1]
	v_pk_fma_f32 v[140:141], v[122:123], v[136:137], v[150:151] op_sel_hi:[1,0,1] neg_lo:[0,0,1] neg_hi:[0,0,1]
	v_pk_fma_f32 v[142:143], v[116:117], v[136:137], v[152:153] op_sel_hi:[1,0,1] neg_lo:[0,0,1] neg_hi:[0,0,1]
	v_pk_fma_f32 v[136:137], v[114:115], v[136:137], v[154:155] op_sel_hi:[1,0,1] neg_lo:[0,0,1] neg_hi:[0,0,1]
	v_exp_f32_e32 v142, v142
	v_exp_f32_e32 v136, v136
	v_exp_f32_e32 v137, v137
	v_exp_f32_e32 v143, v143
	v_exp_f32_e32 v140, v140
	v_exp_f32_e32 v141, v141
	v_exp_f32_e32 v138, v138
	v_exp_f32_e32 v139, v139
	v_pk_add_f32 v[142:143], v[142:143], 1.0 op_sel_hi:[1,0]
	v_pk_add_f32 v[136:137], v[136:137], 1.0 op_sel_hi:[1,0]
	v_pk_add_f32 v[140:141], v[140:141], 1.0 op_sel_hi:[1,0]
	v_rcp_f32_e32 v136, v136
	v_rcp_f32_e32 v137, v137
	v_rcp_f32_e32 v142, v142
	v_rcp_f32_e32 v143, v143
	v_pk_fma_f32 v[124:125], v[124:125], v[134:135], v[68:69] op_sel_hi:[1,0,1]
	v_pk_fma_f32 v[122:123], v[122:123], v[134:135], v[66:67] op_sel_hi:[1,0,1]
	v_pk_fma_f32 v[128:129], v[128:129], v[134:135], v[64:65] op_sel_hi:[1,0,1]
	v_pk_fma_f32 v[126:127], v[126:127], v[134:135], v[62:63] op_sel_hi:[1,0,1]
	v_pk_add_f32 v[138:139], v[138:139], 1.0 op_sel_hi:[1,0]
	v_rcp_f32_e32 v140, v140
	v_rcp_f32_e32 v141, v141
	v_or_b32_e32 v135, 16, v146
	v_rcp_f32_e32 v138, v138
	v_rcp_f32_e32 v139, v139
	v_pk_fma_f32 v[116:117], v[116:117], v[134:135], v[56:57] op_sel_hi:[1,0,1]
	v_pk_fma_f32 v[114:115], v[114:115], v[134:135], v[54:55] op_sel_hi:[1,0,1]
	v_pk_fma_f32 v[120:121], v[120:121], v[134:135], v[52:53] op_sel_hi:[1,0,1]
	v_pk_fma_f32 v[118:119], v[118:119], v[134:135], v[50:51] op_sel_hi:[1,0,1]
	v_pk_mul_f32 v[116:117], v[116:117], v[120:121]
	v_pk_mul_f32 v[114:115], v[114:115], v[118:119]
	v_pk_mul_f32 v[122:123], v[122:123], v[126:127]
	v_pk_mul_f32 v[118:119], v[116:117], v[142:143]
	v_pk_mul_f32 v[116:117], v[114:115], v[136:137]
	v_mad_i64_i32 v[114:115], s[0:1], v135, s13, v[130:131]
	v_pk_mul_f32 v[124:125], v[124:125], v[128:129]
	v_pk_mul_f32 v[122:123], v[122:123], v[140:141]
	v_lshl_add_u64 v[120:121], v[114:115], 0, v[132:133]
	v_cvt_pk_bf16_f32 v114, v122, v123
	v_pk_mul_f32 v[124:125], v[124:125], v[138:139]
	s_nop 0
	v_cvt_pk_bf16_f32 v115, v124, v125
	v_cvt_pk_bf16_f32 v116, v116, v117
	v_cvt_pk_bf16_f32 v117, v118, v119
	flat_store_dwordx4 v[120:121], v[114:117]
	s_nop 1
	v_fmamk_f32 v114, v164, 0x3a000000, v180
	v_cmp_gt_f32_e32 vcc, s73, v114
	v_mul_f32_e32 v115, 0x4b800000, v114
	s_nop 0
	v_cndmask_b32_e32 v114, v114, v115, vcc
	v_rsq_f32_e32 v114, v114
	s_nop 0
	v_mul_f32_e32 v115, 0x45800000, v114
	v_cndmask_b32_e32 v114, v114, v115, vcc
	v_mul_f32_e32 v116, 0xbfb8aa3b, v114
	v_pk_fma_f32 v[118:119], v[108:109], v[116:117], v[148:149] op_sel_hi:[1,0,1] neg_lo:[0,0,1] neg_hi:[0,0,1]
	v_pk_fma_f32 v[120:121], v[106:107], v[116:117], v[150:151] op_sel_hi:[1,0,1] neg_lo:[0,0,1] neg_hi:[0,0,1]
	v_pk_fma_f32 v[122:123], v[100:101], v[116:117], v[152:153] op_sel_hi:[1,0,1] neg_lo:[0,0,1] neg_hi:[0,0,1]
	v_pk_fma_f32 v[116:117], v[98:99], v[116:117], v[154:155] op_sel_hi:[1,0,1] neg_lo:[0,0,1] neg_hi:[0,0,1]
	v_exp_f32_e32 v122, v122
	v_exp_f32_e32 v116, v116
	v_exp_f32_e32 v117, v117
	v_exp_f32_e32 v123, v123
	v_exp_f32_e32 v120, v120
	v_exp_f32_e32 v121, v121
	v_exp_f32_e32 v118, v118
	v_exp_f32_e32 v119, v119
	v_pk_add_f32 v[122:123], v[122:123], 1.0 op_sel_hi:[1,0]
	v_pk_add_f32 v[116:117], v[116:117], 1.0 op_sel_hi:[1,0]
	v_pk_add_f32 v[120:121], v[120:121], 1.0 op_sel_hi:[1,0]
	v_rcp_f32_e32 v116, v116
	v_rcp_f32_e32 v117, v117
	v_rcp_f32_e32 v122, v122
	v_rcp_f32_e32 v123, v123
	v_pk_fma_f32 v[108:109], v[108:109], v[114:115], v[68:69] op_sel_hi:[1,0,1]
	v_pk_fma_f32 v[106:107], v[106:107], v[114:115], v[66:67] op_sel_hi:[1,0,1]
	v_pk_fma_f32 v[112:113], v[112:113], v[114:115], v[64:65] op_sel_hi:[1,0,1]
	v_pk_fma_f32 v[110:111], v[110:111], v[114:115], v[62:63] op_sel_hi:[1,0,1]
	v_pk_add_f32 v[118:119], v[118:119], 1.0 op_sel_hi:[1,0]
	v_rcp_f32_e32 v120, v120
	v_rcp_f32_e32 v121, v121
	v_or_b32_e32 v115, 32, v146
	v_rcp_f32_e32 v118, v118
	v_rcp_f32_e32 v119, v119
	v_pk_fma_f32 v[100:101], v[100:101], v[114:115], v[56:57] op_sel_hi:[1,0,1]
	v_pk_fma_f32 v[98:99], v[98:99], v[114:115], v[54:55] op_sel_hi:[1,0,1]
	v_pk_fma_f32 v[104:105], v[104:105], v[114:115], v[52:53] op_sel_hi:[1,0,1]
	v_pk_fma_f32 v[102:103], v[102:103], v[114:115], v[50:51] op_sel_hi:[1,0,1]
	v_pk_mul_f32 v[100:101], v[100:101], v[104:105]
	v_pk_mul_f32 v[98:99], v[98:99], v[102:103]
	v_pk_mul_f32 v[106:107], v[106:107], v[110:111]
	v_pk_mul_f32 v[102:103], v[100:101], v[122:123]
	v_pk_mul_f32 v[100:101], v[98:99], v[116:117]
	v_mad_i64_i32 v[98:99], s[0:1], v115, s13, v[130:131]
	v_pk_mul_f32 v[108:109], v[108:109], v[112:113]
	v_pk_mul_f32 v[106:107], v[106:107], v[120:121]
	v_lshl_add_u64 v[104:105], v[98:99], 0, v[132:133]
	v_cvt_pk_bf16_f32 v98, v106, v107
	v_pk_mul_f32 v[108:109], v[108:109], v[118:119]
	s_nop 0
	v_cvt_pk_bf16_f32 v99, v108, v109
	v_cvt_pk_bf16_f32 v100, v100, v101
	v_cvt_pk_bf16_f32 v101, v102, v103
	flat_store_dwordx4 v[104:105], v[98:101]
	s_nop 1
	v_fmamk_f32 v98, v163, 0x3a000000, v180
	v_cmp_gt_f32_e32 vcc, s73, v98
	v_mul_f32_e32 v99, 0x4b800000, v98
	s_nop 0
	v_cndmask_b32_e32 v98, v98, v99, vcc
	v_rsq_f32_e32 v98, v98
	s_nop 0
	v_mul_f32_e32 v99, 0x45800000, v98
	v_cndmask_b32_e32 v98, v98, v99, vcc
	v_mul_f32_e32 v100, 0xbfb8aa3b, v98
	v_pk_fma_f32 v[102:103], v[92:93], v[100:101], v[148:149] op_sel_hi:[1,0,1] neg_lo:[0,0,1] neg_hi:[0,0,1]
	v_pk_fma_f32 v[104:105], v[90:91], v[100:101], v[150:151] op_sel_hi:[1,0,1] neg_lo:[0,0,1] neg_hi:[0,0,1]
	v_pk_fma_f32 v[106:107], v[84:85], v[100:101], v[152:153] op_sel_hi:[1,0,1] neg_lo:[0,0,1] neg_hi:[0,0,1]
	v_pk_fma_f32 v[100:101], v[82:83], v[100:101], v[154:155] op_sel_hi:[1,0,1] neg_lo:[0,0,1] neg_hi:[0,0,1]
	v_exp_f32_e32 v106, v106
	v_exp_f32_e32 v100, v100
	v_exp_f32_e32 v101, v101
	v_exp_f32_e32 v107, v107
	v_exp_f32_e32 v104, v104
	v_exp_f32_e32 v105, v105
	v_exp_f32_e32 v102, v102
	v_exp_f32_e32 v103, v103
	v_pk_add_f32 v[106:107], v[106:107], 1.0 op_sel_hi:[1,0]
	v_pk_add_f32 v[100:101], v[100:101], 1.0 op_sel_hi:[1,0]
	v_pk_add_f32 v[104:105], v[104:105], 1.0 op_sel_hi:[1,0]
	v_rcp_f32_e32 v100, v100
	v_rcp_f32_e32 v101, v101
	v_rcp_f32_e32 v106, v106
	v_rcp_f32_e32 v107, v107
	v_pk_fma_f32 v[92:93], v[92:93], v[98:99], v[68:69] op_sel_hi:[1,0,1]
	v_pk_fma_f32 v[90:91], v[90:91], v[98:99], v[66:67] op_sel_hi:[1,0,1]
	v_pk_fma_f32 v[96:97], v[96:97], v[98:99], v[64:65] op_sel_hi:[1,0,1]
	v_pk_fma_f32 v[94:95], v[94:95], v[98:99], v[62:63] op_sel_hi:[1,0,1]
	v_pk_add_f32 v[102:103], v[102:103], 1.0 op_sel_hi:[1,0]
	v_rcp_f32_e32 v104, v104
	v_rcp_f32_e32 v105, v105
	v_or_b32_e32 v99, 48, v146
	v_rcp_f32_e32 v102, v102
	v_rcp_f32_e32 v103, v103
	v_pk_fma_f32 v[84:85], v[84:85], v[98:99], v[56:57] op_sel_hi:[1,0,1]
	v_pk_fma_f32 v[82:83], v[82:83], v[98:99], v[54:55] op_sel_hi:[1,0,1]
	v_pk_fma_f32 v[88:89], v[88:89], v[98:99], v[52:53] op_sel_hi:[1,0,1]
	v_pk_fma_f32 v[86:87], v[86:87], v[98:99], v[50:51] op_sel_hi:[1,0,1]
	v_pk_mul_f32 v[84:85], v[84:85], v[88:89]
	v_pk_mul_f32 v[82:83], v[82:83], v[86:87]
	v_pk_mul_f32 v[90:91], v[90:91], v[94:95]
	v_pk_mul_f32 v[86:87], v[84:85], v[106:107]
	v_pk_mul_f32 v[84:85], v[82:83], v[100:101]
	v_mad_i64_i32 v[82:83], s[0:1], v99, s13, v[130:131]
	v_pk_mul_f32 v[92:93], v[92:93], v[96:97]
	v_pk_mul_f32 v[90:91], v[90:91], v[104:105]
	v_lshl_add_u64 v[88:89], v[82:83], 0, v[132:133]
	v_cvt_pk_bf16_f32 v82, v90, v91
	v_pk_mul_f32 v[92:93], v[92:93], v[102:103]
	s_nop 0
	v_cvt_pk_bf16_f32 v83, v92, v93
	v_cvt_pk_bf16_f32 v84, v84, v85
	v_cvt_pk_bf16_f32 v85, v86, v87
	flat_store_dwordx4 v[88:89], v[82:85]
	s_nop 1
	v_fmamk_f32 v82, v162, 0x3a000000, v180
	v_cmp_gt_f32_e32 vcc, s73, v82
	v_mul_f32_e32 v84, 0x4b800000, v82
	v_add_u32_e32 v83, 0x80, v146
	v_cndmask_b32_e32 v82, v82, v84, vcc
	v_rsq_f32_e32 v82, v82
	s_nop 0
	v_mul_f32_e32 v84, 0x45800000, v82
	v_cndmask_b32_e32 v82, v82, v84, vcc
	v_mul_f32_e32 v84, 0xbfb8aa3b, v82
	v_pk_fma_f32 v[86:87], v[76:77], v[84:85], v[148:149] op_sel_hi:[1,0,1] neg_lo:[0,0,1] neg_hi:[0,0,1]
	v_pk_fma_f32 v[88:89], v[74:75], v[84:85], v[150:151] op_sel_hi:[1,0,1] neg_lo:[0,0,1] neg_hi:[0,0,1]
	v_pk_fma_f32 v[90:91], v[60:61], v[84:85], v[152:153] op_sel_hi:[1,0,1] neg_lo:[0,0,1] neg_hi:[0,0,1]
	v_pk_fma_f32 v[84:85], v[58:59], v[84:85], v[154:155] op_sel_hi:[1,0,1] neg_lo:[0,0,1] neg_hi:[0,0,1]
	v_exp_f32_e32 v90, v90
	v_exp_f32_e32 v84, v84
	v_exp_f32_e32 v85, v85
	v_exp_f32_e32 v91, v91
	v_exp_f32_e32 v88, v88
	v_exp_f32_e32 v89, v89
	v_exp_f32_e32 v86, v86
	v_exp_f32_e32 v87, v87
	v_pk_add_f32 v[90:91], v[90:91], 1.0 op_sel_hi:[1,0]
	v_pk_add_f32 v[84:85], v[84:85], 1.0 op_sel_hi:[1,0]
	v_pk_add_f32 v[88:89], v[88:89], 1.0 op_sel_hi:[1,0]
	v_rcp_f32_e32 v84, v84
	v_rcp_f32_e32 v85, v85
	v_rcp_f32_e32 v90, v90
	v_rcp_f32_e32 v91, v91
	v_pk_add_f32 v[86:87], v[86:87], 1.0 op_sel_hi:[1,0]
	v_rcp_f32_e32 v88, v88
	v_rcp_f32_e32 v89, v89
	v_rcp_f32_e32 v86, v86
	v_rcp_f32_e32 v87, v87
	v_pk_fma_f32 v[60:61], v[60:61], v[82:83], v[56:57] op_sel_hi:[1,0,1]
	v_pk_fma_f32 v[58:59], v[58:59], v[82:83], v[54:55] op_sel_hi:[1,0,1]
	v_pk_fma_f32 v[72:73], v[72:73], v[82:83], v[52:53] op_sel_hi:[1,0,1]
	v_pk_fma_f32 v[70:71], v[70:71], v[82:83], v[50:51] op_sel_hi:[1,0,1]
	v_pk_fma_f32 v[74:75], v[74:75], v[82:83], v[66:67] op_sel_hi:[1,0,1]
	v_pk_fma_f32 v[78:79], v[78:79], v[82:83], v[62:63] op_sel_hi:[1,0,1]
	v_pk_mul_f32 v[58:59], v[58:59], v[70:71]
	v_pk_mul_f32 v[60:61], v[60:61], v[72:73]
	v_pk_fma_f32 v[76:77], v[76:77], v[82:83], v[68:69] op_sel_hi:[1,0,1]
	v_pk_fma_f32 v[80:81], v[80:81], v[82:83], v[64:65] op_sel_hi:[1,0,1]
	v_pk_mul_f32 v[74:75], v[74:75], v[78:79]
	v_pk_mul_f32 v[70:71], v[60:61], v[90:91]
	v_pk_mul_f32 v[60:61], v[58:59], v[84:85]
	v_mad_i64_i32 v[58:59], s[0:1], v83, s13, v[130:131]
	v_pk_mul_f32 v[76:77], v[76:77], v[80:81]
	v_pk_mul_f32 v[74:75], v[74:75], v[88:89]
	v_lshl_add_u64 v[72:73], v[58:59], 0, v[132:133]
	v_cvt_pk_bf16_f32 v58, v74, v75
	v_pk_mul_f32 v[76:77], v[76:77], v[86:87]
	s_nop 0
	v_cvt_pk_bf16_f32 v59, v76, v77
	v_cvt_pk_bf16_f32 v60, v60, v61
	v_cvt_pk_bf16_f32 v61, v70, v71
	flat_store_dwordx4 v[72:73], v[58:61]
	s_nop 1
	v_fmamk_f32 v58, v161, 0x3a000000, v180
	v_cmp_gt_f32_e32 vcc, s73, v58
	v_mul_f32_e32 v59, 0x4b800000, v58
	s_nop 0
	v_cndmask_b32_e32 v58, v58, v59, vcc
	v_rsq_f32_e32 v58, v58
	s_nop 0
	v_mul_f32_e32 v59, 0x45800000, v58
	v_cndmask_b32_e32 v58, v58, v59, vcc
	v_mul_f32_e32 v60, 0xbfb8aa3b, v58
	v_pk_fma_f32 v[70:71], v[44:45], v[60:61], v[148:149] op_sel_hi:[1,0,1] neg_lo:[0,0,1] neg_hi:[0,0,1]
	v_pk_fma_f32 v[72:73], v[42:43], v[60:61], v[150:151] op_sel_hi:[1,0,1] neg_lo:[0,0,1] neg_hi:[0,0,1]
	v_pk_fma_f32 v[74:75], v[36:37], v[60:61], v[152:153] op_sel_hi:[1,0,1] neg_lo:[0,0,1] neg_hi:[0,0,1]
	v_pk_fma_f32 v[60:61], v[34:35], v[60:61], v[154:155] op_sel_hi:[1,0,1] neg_lo:[0,0,1] neg_hi:[0,0,1]
	v_exp_f32_e32 v74, v74
	v_exp_f32_e32 v60, v60
	v_exp_f32_e32 v61, v61
	v_exp_f32_e32 v75, v75
	v_exp_f32_e32 v72, v72
	v_exp_f32_e32 v73, v73
	v_exp_f32_e32 v70, v70
	v_exp_f32_e32 v71, v71
	v_pk_add_f32 v[74:75], v[74:75], 1.0 op_sel_hi:[1,0]
	v_pk_add_f32 v[60:61], v[60:61], 1.0 op_sel_hi:[1,0]
	v_pk_add_f32 v[72:73], v[72:73], 1.0 op_sel_hi:[1,0]
	v_rcp_f32_e32 v60, v60
	v_rcp_f32_e32 v61, v61
	v_rcp_f32_e32 v74, v74
	v_rcp_f32_e32 v75, v75
	v_pk_fma_f32 v[44:45], v[44:45], v[58:59], v[68:69] op_sel_hi:[1,0,1]
	v_pk_fma_f32 v[42:43], v[42:43], v[58:59], v[66:67] op_sel_hi:[1,0,1]
	v_pk_fma_f32 v[48:49], v[48:49], v[58:59], v[64:65] op_sel_hi:[1,0,1]
	v_pk_fma_f32 v[46:47], v[46:47], v[58:59], v[62:63] op_sel_hi:[1,0,1]
	v_pk_add_f32 v[70:71], v[70:71], 1.0 op_sel_hi:[1,0]
	v_rcp_f32_e32 v72, v72
	v_rcp_f32_e32 v73, v73
	v_add_u32_e32 v59, 0x90, v146
	v_rcp_f32_e32 v70, v70
	v_rcp_f32_e32 v71, v71
	v_pk_fma_f32 v[36:37], v[36:37], v[58:59], v[56:57] op_sel_hi:[1,0,1]
	v_pk_fma_f32 v[34:35], v[34:35], v[58:59], v[54:55] op_sel_hi:[1,0,1]
	v_pk_fma_f32 v[40:41], v[40:41], v[58:59], v[52:53] op_sel_hi:[1,0,1]
	v_pk_fma_f32 v[38:39], v[38:39], v[58:59], v[50:51] op_sel_hi:[1,0,1]
	v_pk_mul_f32 v[36:37], v[36:37], v[40:41]
	v_pk_mul_f32 v[34:35], v[34:35], v[38:39]
	v_pk_mul_f32 v[42:43], v[42:43], v[46:47]
	v_pk_mul_f32 v[38:39], v[36:37], v[74:75]
	v_pk_mul_f32 v[36:37], v[34:35], v[60:61]
	v_mad_i64_i32 v[34:35], s[0:1], v59, s13, v[130:131]
	v_pk_mul_f32 v[44:45], v[44:45], v[48:49]
	v_pk_mul_f32 v[42:43], v[42:43], v[72:73]
	v_lshl_add_u64 v[40:41], v[34:35], 0, v[132:133]
	v_cvt_pk_bf16_f32 v34, v42, v43
	v_pk_mul_f32 v[44:45], v[44:45], v[70:71]
	s_nop 0
	v_cvt_pk_bf16_f32 v35, v44, v45
	v_cvt_pk_bf16_f32 v36, v36, v37
	v_cvt_pk_bf16_f32 v37, v38, v39
	flat_store_dwordx4 v[40:41], v[34:37]
	s_nop 1
	v_fmamk_f32 v34, v147, 0x3a000000, v180
	v_cmp_gt_f32_e32 vcc, s73, v34
	v_mul_f32_e32 v35, 0x4b800000, v34
	s_nop 0
	v_cndmask_b32_e32 v34, v34, v35, vcc
	v_rsq_f32_e32 v34, v34
	s_nop 0
	v_mul_f32_e32 v35, 0x45800000, v34
	v_cndmask_b32_e32 v34, v34, v35, vcc
	v_mul_f32_e32 v36, 0xbfb8aa3b, v34
	v_pk_fma_f32 v[38:39], v[28:29], v[36:37], v[148:149] op_sel_hi:[1,0,1] neg_lo:[0,0,1] neg_hi:[0,0,1]
	v_pk_fma_f32 v[40:41], v[26:27], v[36:37], v[150:151] op_sel_hi:[1,0,1] neg_lo:[0,0,1] neg_hi:[0,0,1]
	v_pk_fma_f32 v[42:43], v[20:21], v[36:37], v[152:153] op_sel_hi:[1,0,1] neg_lo:[0,0,1] neg_hi:[0,0,1]
	v_pk_fma_f32 v[36:37], v[18:19], v[36:37], v[154:155] op_sel_hi:[1,0,1] neg_lo:[0,0,1] neg_hi:[0,0,1]
	v_exp_f32_e32 v42, v42
	v_exp_f32_e32 v36, v36
	v_exp_f32_e32 v37, v37
	v_exp_f32_e32 v43, v43
	v_exp_f32_e32 v40, v40
	v_exp_f32_e32 v41, v41
	v_exp_f32_e32 v38, v38
	v_exp_f32_e32 v39, v39
	v_pk_add_f32 v[42:43], v[42:43], 1.0 op_sel_hi:[1,0]
	v_pk_add_f32 v[36:37], v[36:37], 1.0 op_sel_hi:[1,0]
	v_pk_add_f32 v[40:41], v[40:41], 1.0 op_sel_hi:[1,0]
	v_rcp_f32_e32 v36, v36
	v_rcp_f32_e32 v37, v37
	v_rcp_f32_e32 v42, v42
	v_rcp_f32_e32 v43, v43
	v_pk_fma_f32 v[28:29], v[28:29], v[34:35], v[68:69] op_sel_hi:[1,0,1]
	v_pk_fma_f32 v[26:27], v[26:27], v[34:35], v[66:67] op_sel_hi:[1,0,1]
	v_pk_fma_f32 v[32:33], v[32:33], v[34:35], v[64:65] op_sel_hi:[1,0,1]
	v_pk_fma_f32 v[30:31], v[30:31], v[34:35], v[62:63] op_sel_hi:[1,0,1]
	v_pk_add_f32 v[38:39], v[38:39], 1.0 op_sel_hi:[1,0]
	v_rcp_f32_e32 v40, v40
	v_rcp_f32_e32 v41, v41
	v_add_u32_e32 v35, 0xa0, v146
	v_rcp_f32_e32 v38, v38
	v_rcp_f32_e32 v39, v39
	v_pk_fma_f32 v[20:21], v[20:21], v[34:35], v[56:57] op_sel_hi:[1,0,1]
	v_pk_fma_f32 v[18:19], v[18:19], v[34:35], v[54:55] op_sel_hi:[1,0,1]
	v_pk_fma_f32 v[24:25], v[24:25], v[34:35], v[52:53] op_sel_hi:[1,0,1]
	v_pk_fma_f32 v[22:23], v[22:23], v[34:35], v[50:51] op_sel_hi:[1,0,1]
	v_pk_mul_f32 v[20:21], v[20:21], v[24:25]
	v_pk_mul_f32 v[18:19], v[18:19], v[22:23]
	v_pk_mul_f32 v[26:27], v[26:27], v[30:31]
	v_pk_mul_f32 v[22:23], v[20:21], v[42:43]
	v_pk_mul_f32 v[20:21], v[18:19], v[36:37]
	v_mad_i64_i32 v[18:19], s[0:1], v35, s13, v[130:131]
	v_pk_mul_f32 v[28:29], v[28:29], v[32:33]
	v_pk_mul_f32 v[26:27], v[26:27], v[40:41]
	v_lshl_add_u64 v[24:25], v[18:19], 0, v[132:133]
	v_cvt_pk_bf16_f32 v18, v26, v27
	v_pk_mul_f32 v[28:29], v[28:29], v[38:39]
	s_nop 0
	v_cvt_pk_bf16_f32 v19, v28, v29
	v_cvt_pk_bf16_f32 v20, v20, v21
	v_cvt_pk_bf16_f32 v21, v22, v23
	flat_store_dwordx4 v[24:25], v[18:21]
	s_nop 1
	v_fmamk_f32 v18, v166, 0x3a000000, v180
	v_cmp_gt_f32_e32 vcc, s73, v18
	v_mul_f32_e32 v19, 0x4b800000, v18
	s_nop 0
	v_cndmask_b32_e32 v18, v18, v19, vcc
	v_rsq_f32_e32 v18, v18
	s_nop 0
	v_mul_f32_e32 v19, 0x45800000, v18
	v_cndmask_b32_e32 v18, v18, v19, vcc
	v_mul_f32_e32 v20, 0xbfb8aa3b, v18
	v_pk_fma_f32 v[22:23], v[12:13], v[20:21], v[148:149] op_sel_hi:[1,0,1] neg_lo:[0,0,1] neg_hi:[0,0,1]
	v_pk_fma_f32 v[24:25], v[10:11], v[20:21], v[150:151] op_sel_hi:[1,0,1] neg_lo:[0,0,1] neg_hi:[0,0,1]
	v_pk_fma_f32 v[26:27], v[4:5], v[20:21], v[152:153] op_sel_hi:[1,0,1] neg_lo:[0,0,1] neg_hi:[0,0,1]
	v_pk_fma_f32 v[20:21], v[2:3], v[20:21], v[154:155] op_sel_hi:[1,0,1] neg_lo:[0,0,1] neg_hi:[0,0,1]
	v_exp_f32_e32 v26, v26
	v_exp_f32_e32 v20, v20
	v_exp_f32_e32 v21, v21
	v_exp_f32_e32 v27, v27
	v_exp_f32_e32 v24, v24
	v_exp_f32_e32 v25, v25
	v_exp_f32_e32 v22, v22
	v_exp_f32_e32 v23, v23
	v_pk_add_f32 v[26:27], v[26:27], 1.0 op_sel_hi:[1,0]
	v_pk_add_f32 v[20:21], v[20:21], 1.0 op_sel_hi:[1,0]
	v_rcp_f32_e32 v26, v26
	v_rcp_f32_e32 v20, v20
	v_rcp_f32_e32 v21, v21
	v_rcp_f32_e32 v27, v27
	v_pk_fma_f32 v[12:13], v[12:13], v[18:19], v[68:69] op_sel_hi:[1,0,1]
	v_pk_fma_f32 v[10:11], v[10:11], v[18:19], v[66:67] op_sel_hi:[1,0,1]
	v_pk_fma_f32 v[16:17], v[16:17], v[18:19], v[64:65] op_sel_hi:[1,0,1]
	v_pk_fma_f32 v[14:15], v[14:15], v[18:19], v[62:63] op_sel_hi:[1,0,1]
	v_pk_add_f32 v[22:23], v[22:23], 1.0 op_sel_hi:[1,0]
	v_pk_add_f32 v[24:25], v[24:25], 1.0 op_sel_hi:[1,0]
	v_add_u32_e32 v19, 0xb0, v146
	v_rcp_f32_e32 v24, v24
	v_rcp_f32_e32 v25, v25
	v_rcp_f32_e32 v22, v22
	v_rcp_f32_e32 v23, v23
	v_pk_fma_f32 v[4:5], v[4:5], v[18:19], v[56:57] op_sel_hi:[1,0,1]
	v_pk_fma_f32 v[2:3], v[2:3], v[18:19], v[54:55] op_sel_hi:[1,0,1]
	v_pk_fma_f32 v[8:9], v[8:9], v[18:19], v[52:53] op_sel_hi:[1,0,1]
	v_pk_fma_f32 v[6:7], v[6:7], v[18:19], v[50:51] op_sel_hi:[1,0,1]
	v_pk_mul_f32 v[4:5], v[4:5], v[8:9]
	v_pk_mul_f32 v[2:3], v[2:3], v[6:7]
	v_pk_mul_f32 v[6:7], v[4:5], v[26:27]
	v_pk_mul_f32 v[4:5], v[2:3], v[20:21]
	v_mad_i64_i32 v[2:3], s[0:1], v19, s13, v[130:131]
	v_pk_mul_f32 v[10:11], v[10:11], v[14:15]
	v_pk_mul_f32 v[12:13], v[12:13], v[16:17]
	v_lshl_add_u64 v[8:9], v[2:3], 0, v[132:133]
	s_andn2_b64 vcc, exec, s[6:7]
	v_pk_mul_f32 v[12:13], v[12:13], v[22:23]
	v_pk_mul_f32 v[10:11], v[10:11], v[24:25]
	s_nop 0
	v_cvt_pk_bf16_f32 v2, v10, v11
	v_cvt_pk_bf16_f32 v3, v12, v13
	v_cvt_pk_bf16_f32 v4, v4, v5
	v_cvt_pk_bf16_f32 v5, v6, v7
	flat_store_dwordx4 v[8:9], v[2:5]
	s_cbranch_vccnz .LBB0_1145
	s_and_b64 vcc, exec, s[2:3]
	s_cbranch_vccnz .LBB0_1144
	s_barrier
	s_branch .LBB0_1144
